# V-transpose prep phase: all 16 row loads of a tile issued before the LDS writes (counted vmcnt) instead of load/wait/write one at a time
# baseline (speedup 1.0000x reference)
; #define LDS_WAIT() asm volatile("s_waitcnt lgkmcnt(0)" ::: "memory")
; DI void prep_phase(PP P, int l, unsigned char* lds, int G, int cid) {
;     ...
;     for (int it = gw; it < 2048; it += NGW) {
;         const int bh = it >> 6, tt = it & 63, b = bh >> 3, h = bh & 7;
; #pragma unroll
;         for (int i = 0; i < 16; ++i) { const int t = 4 * i + (lane >> 4), ch = lane & 15;
;             const u32x4 w = *(const u32x4*)(Zv + ((size_t)b * SEQ + tt * 64 + t) * 1024 + h * 128 + ch * 8);
;             *(u32x4*)(tile + t * 136 + ch * 8) = w; }
;         LDS_WAIT();
.LBB0_253:
	v_ashrrev_i32_e32 v40, 9, v3
	v_ashrrev_i32_e32 v41, 31, v40
	v_ashrrev_i32_e32 v38, 6, v3
	v_lshlrev_b64 v[44:45], 12, v[40:41]
	v_lshlrev_b32_e32 v0, 6, v3
	s_movk_i32 s6, 0xfc0
	v_and_or_b32 v15, v0, s6, v44
	v_lshlrev_b32_e32 v0, 8, v38
	v_and_b32_e32 v0, 0x700, v0
	v_or_b32_e32 v44, v15, v2
	v_lshl_add_u64 v[46:47], v[4:5], 0, v[0:1]
	v_lshlrev_b64 v[40:41], 11, v[44:45]
	v_lshl_add_u64 v[40:41], v[46:47], 0, v[40:41]
	global_load_dwordx4 v[48:51], v[40:41], off
	v_or_b32_e32 v44, v15, v6
	v_ashrrev_i32_e32 v39, 31, v38
	v_lshlrev_b32_e32 v13, 1, v7
	v_lshlrev_b64 v[38:39], 20, v[38:39]
	s_movk_i32 s6, 0x1f80
	v_and_or_b32 v38, v13, s6, v38
	v_lshl_add_u64 v[38:39], v[36:37], 0, v[38:39]
	s_mov_b32 s6, 0
	v_lshlrev_b64 v[40:41], 11, v[44:45]
	v_lshl_add_u64 v[40:41], v[46:47], 0, v[40:41]
	global_load_dwordx4 v[52:55], v[40:41], off
	v_or_b32_e32 v44, v15, v8
	v_lshlrev_b64 v[40:41], 11, v[44:45]
	v_lshl_add_u64 v[40:41], v[46:47], 0, v[40:41]
	global_load_dwordx4 v[56:59], v[40:41], off
	v_or_b32_e32 v44, v15, v10
	v_lshlrev_b64 v[40:41], 11, v[44:45]
	v_lshl_add_u64 v[40:41], v[46:47], 0, v[40:41]
	global_load_dwordx4 v[60:63], v[40:41], off
	v_or_b32_e32 v44, v15, v12
	v_lshlrev_b64 v[40:41], 11, v[44:45]
	v_lshl_add_u64 v[40:41], v[46:47], 0, v[40:41]
	global_load_dwordx4 v[64:67], v[40:41], off
	v_or_b32_e32 v44, v15, v14
	v_lshlrev_b64 v[40:41], 11, v[44:45]
	v_lshl_add_u64 v[40:41], v[46:47], 0, v[40:41]
	global_load_dwordx4 v[68:71], v[40:41], off
	v_or_b32_e32 v44, v15, v16
	v_lshlrev_b64 v[40:41], 11, v[44:45]
	v_lshl_add_u64 v[40:41], v[46:47], 0, v[40:41]
	global_load_dwordx4 v[72:75], v[40:41], off
	v_or_b32_e32 v44, v15, v18
	v_lshlrev_b64 v[40:41], 11, v[44:45]
	v_lshl_add_u64 v[40:41], v[46:47], 0, v[40:41]
	global_load_dwordx4 v[76:79], v[40:41], off
	v_or_b32_e32 v44, v15, v20
	v_lshlrev_b64 v[40:41], 11, v[44:45]
	v_lshl_add_u64 v[40:41], v[46:47], 0, v[40:41]
	global_load_dwordx4 v[80:83], v[40:41], off
	v_or_b32_e32 v44, v15, v22
	v_lshlrev_b64 v[40:41], 11, v[44:45]
	v_lshl_add_u64 v[40:41], v[46:47], 0, v[40:41]
	global_load_dwordx4 v[84:87], v[40:41], off
	v_or_b32_e32 v44, v15, v24
	v_lshlrev_b64 v[40:41], 11, v[44:45]
	v_lshl_add_u64 v[40:41], v[46:47], 0, v[40:41]
	global_load_dwordx4 v[88:91], v[40:41], off
	v_or_b32_e32 v44, v15, v26
	v_lshlrev_b64 v[40:41], 11, v[44:45]
	v_lshl_add_u64 v[40:41], v[46:47], 0, v[40:41]
	global_load_dwordx4 v[92:95], v[40:41], off
	v_or_b32_e32 v44, v15, v28
	v_lshlrev_b64 v[40:41], 11, v[44:45]
	v_lshl_add_u64 v[40:41], v[46:47], 0, v[40:41]
	global_load_dwordx4 v[96:99], v[40:41], off
	v_or_b32_e32 v44, v15, v30
	v_lshlrev_b64 v[40:41], 11, v[44:45]
	v_lshl_add_u64 v[40:41], v[46:47], 0, v[40:41]
	global_load_dwordx4 v[100:103], v[40:41], off
	v_or_b32_e32 v44, v15, v32
	v_lshlrev_b64 v[40:41], 11, v[44:45]
	v_lshl_add_u64 v[40:41], v[46:47], 0, v[40:41]
	global_load_dwordx4 v[104:107], v[40:41], off
	v_or_b32_e32 v44, v15, v34
	v_lshlrev_b64 v[40:41], 11, v[44:45]
	v_lshl_add_u64 v[40:41], v[46:47], 0, v[40:41]
	global_load_dwordx4 v[108:111], v[40:41], off
	s_waitcnt vmcnt(15)
	ds_write_b128 v11, v[48:51]
	s_waitcnt vmcnt(14)
	ds_write_b128 v11, v[52:55] offset:1088
	s_waitcnt vmcnt(13)
	ds_write_b128 v11, v[56:59] offset:2176
	s_waitcnt vmcnt(12)
	ds_write_b128 v11, v[60:63] offset:3264
	s_waitcnt vmcnt(11)
	ds_write_b128 v11, v[64:67] offset:4352
	s_waitcnt vmcnt(10)
	ds_write_b128 v11, v[68:71] offset:5440
	s_waitcnt vmcnt(9)
	ds_write_b128 v11, v[72:75] offset:6528
	s_waitcnt vmcnt(8)
	ds_write_b128 v11, v[76:79] offset:7616
	s_waitcnt vmcnt(7)
	ds_write_b128 v11, v[80:83] offset:8704
	s_waitcnt vmcnt(6)
	ds_write_b128 v11, v[84:87] offset:9792
	s_waitcnt vmcnt(5)
	ds_write_b128 v11, v[88:91] offset:10880
	s_waitcnt vmcnt(4)
	ds_write_b128 v11, v[92:95] offset:11968
	s_waitcnt vmcnt(3)
	ds_write_b128 v11, v[96:99] offset:13056
	s_waitcnt vmcnt(2)
	ds_write_b128 v11, v[100:103] offset:14144
	s_waitcnt vmcnt(1)
	ds_write_b128 v11, v[104:107] offset:15232
	s_waitcnt vmcnt(0)
	ds_write_b128 v11, v[108:111] offset:16320
	s_waitcnt lgkmcnt(0)
